# y normalisation pass (phase 6) folded into the out-projection GEMM as per-row f32 accumulator scaling at the K midpoint and before the epilogue; one grid barrier fewer
# speedup vs baseline: 1.0220x; 1.0078x over previous
; #define PG8_WAIT_V(n) asm volatile("s_waitcnt vmcnt(" #n ")" ::: "memory")
; #define PG8_BAR __builtin_amdgcn_s_barrier()
; template <class Epi, class Sched, bool ALIGN_EPI = false, bool SP2 = false>
; __device__ __forceinline__ void gemm_phase(PG8_LAS unsigned char* lds, const Gemm g, const Sched& S, const Epi& E, int tid_in) {
;     ...
;     for (int i = 0; i < 2; ++i) { int R, C; stage_rc(tid * 16 + i * 8192, R, C); const int Rb = Epi::PERM ? ((R & ~31) + perm32(R & 31)) : R;
;         voffA[i] = (unsigned)(R * K + C) * 2u; voffB[i] = (unsigned)(Rb * K + C) * 2u; }
;     const size_t kstep = (size_t)(BK * 2);
;     const size_t hstep = (size_t)HALF * K * 2;
;     const size_t tstep = 2 * hstep;
;     const unsigned ldsw = (unsigned)wid * 1024u;
;     const int aoff = lds_byte(wr * 64 + fr, fq * 8), boff = lds_byte(wc * 32 + fr, fq * 8);
;     ...
;     Unit cur, nxt; int ui = 0;
;     if (!S.next(0, cur)) return;
;     f32x4 acc[2][2][4][2];
; #pragma unroll
;     for (int a = 0; a < 2; ++a)
; #pragma unroll
;         for (int b = 0; b < 2; ++b)
; #pragma unroll
;             for (int m = 0; m < 4; ++m)
; #pragma unroll
;                 for (int n = 0; n < 2; ++n) acc[a][b][m][n] = (f32x4){0.f, 0.f, 0.f, 0.f};
;     bf16x8 At[4][2], B0[2][2], B1[2][2];
;     const char* cA = (const char*)g.A + (size_t)cur.pm * tstep; const char* cB = (const char*)g.Bt + (size_t)cur.pn * tstep;
;     S.a_ready(cur);
;     if constexpr (SP2) {
;         PG8_STAGE(PG8_SB(0, 0), cB, voffB); PG8_STAGE(PG8_SB(0, 1), cB + hstep, voffB); PG8_STAGE(PG8_SA(0, 0), cA, voffA); PG8_STAGE(PG8_SA(0, 1), cA + hstep, voffA);
;         if (wr == 1) PG8_BAR;
;         PG8_WAIT_V(2); PG8_BAR;
;         PG8_STAGE(PG8_SB(1, 0), cB + kstep, voffB); PG8_STAGE(PG8_SA(1, 0), cA + kstep, voffA); PG8_STAGE(PG8_SB(1, 1), cB + hstep + kstep, voffB);
;         PG8_WAIT_V(6); PG8_BAR;
;     } else {
;         PG8_STAGE(PG8_SB(0, 0), cB, voffB); PG8_STAGE(PG8_SA(0, 0), cA, voffA); PG8_STAGE(PG8_SB(0, 1), cB + hstep, voffB); PG8_STAGE(PG8_SA(0, 1), cA + hstep, voffA);
;         if (wr == 1) PG8_BAR;
;         PG8_WAIT_V(4); PG8_BAR;
;         PG8_STAGE(PG8_SB(1, 0), cB + kstep, voffB); PG8_STAGE(PG8_SA(1, 0), cA + kstep, voffA); PG8_STAGE(PG8_SB(1, 1), cB + hstep + kstep, voffB);
;         PG8_WAIT_V(6); PG8_BAR;
.LBB0_430:
	s_andn2_b64 vcc, exec, s[2:3]
	v_mov_b32_e32 v207, v208
	s_cbranch_vccnz .LBB0_478
	v_bfe_i32 v2, v12, 27, 1
	v_lshlrev_b32_e32 v0, 4, v12
	v_lshrrev_b32_e32 v2, 22, v2
	v_add_u32_e32 v2, v0, v2
	v_and_b32_e32 v2, 0xfffffc00, v2
	v_sub_u32_e32 v2, v0, v2
	v_ashrrev_i32_e32 v1, 31, v12
	v_lshrrev_b32_e32 v3, 4, v2
	v_lshrrev_b32_e32 v1, 26, v1
	v_bitop3_b32 v2, v3, v2, 32 bitop3:0x6c
	s_ashr_i32 s15, s34, 8
	s_ashr_i32 s14, s34, 6
	v_add_u32_e32 v1, v12, v1
	v_ashrrev_i32_e32 v4, 31, v2
	s_cmp_eq_u32 s48, 7
	v_ashrrev_i32_e32 v1, 6, v1
	v_lshrrev_b32_e32 v4, 26, v4
	s_cselect_b64 s[30:31], -1, 0
	s_cselect_b32 s101, 16, 0x7fffffff
	v_lshlrev_b32_e32 v3, 3, v1
	v_add_u32_e32 v4, v2, v4
	s_and_b64 s[2:3], s[30:31], exec
	v_and_b32_e32 v3, -16, v3
	v_ashrrev_i32_e32 v5, 6, v4
	v_lshlrev_b32_e32 v1, 5, v1
	s_movk_i32 s2, 0x1600
	v_add_u32_e32 v3, v5, v3
	v_and_b32_e32 v13, 32, v1
	v_and_b32_e32 v1, 0xc0, v4
	s_cselect_b32 s35, 0x800, s2
	v_sub_u32_e32 v1, v2, v1
	v_lshlrev_b32_e32 v2, 1, v3
	v_lshrrev_b32_e32 v4, 2, v3
	v_and_b32_e32 v5, 3, v5
	s_mov_b32 s2, 0x7fffe0
	v_ashrrev_i16_sdwa v1, v235, sext(v1) dst_sel:DWORD dst_unused:UNUSED_PAD src0_sel:DWORD src1_sel:BYTE_0
	v_and_b32_e32 v2, 24, v2
	v_and_b32_e32 v4, 4, v4
	v_and_or_b32 v5, v3, s2, v5
	v_bfe_i32 v14, v1, 0, 16
	v_or3_b32 v2, v5, v4, v2
	v_add_u32_e32 v1, v13, v14
	v_mul_lo_u32 v15, v3, s35
	v_mul_u32_u24_e32 v2, s35, v2
	v_add_u32_e32 v0, 0x2000, v0
	v_add_lshl_u32 v212, v1, v15, 1
	v_add_lshl_u32 v192, v2, v1, 1
	v_ashrrev_i32_e32 v1, 31, v0
	v_lshrrev_b32_e32 v1, 22, v1
	v_add_u32_e32 v1, v0, v1
	v_ashrrev_i32_e32 v1, 10, v1
	v_mul_i32_i24_e32 v2, 0x400, v1
	v_sub_u32_e32 v0, v0, v2
	v_lshrrev_b32_e32 v2, 4, v0
	v_bitop3_b32 v0, v2, v0, 32 bitop3:0x6c
	v_ashrrev_i32_e32 v3, 31, v0
	v_lshrrev_b32_e32 v3, 26, v3
	v_lshlrev_b32_e32 v2, 3, v1
	v_add_u32_e32 v3, v0, v3
	v_and_b32_e32 v2, -16, v2
	v_ashrrev_i32_e32 v4, 6, v3
	v_add_u32_e32 v2, v4, v2
	v_and_b32_e32 v4, 3, v4
	v_and_or_b32 v4, v2, s2, v4
	s_mov_b32 s2, 0x5e00000
	s_cselect_b32 s8, s27, s25
	s_cselect_b32 s9, s26, s24
	s_cselect_b32 s24, s2, 0x9200000
	s_lshl_b32 s46, s35, 8
	s_lshl_b32 s23, s35, 9
	s_lshl_b32 s50, s14, 10
	s_and_b64 s[2:3], s[28:29], exec
	s_cselect_b32 s2, 0x3400000, s24
	v_lshlrev_b32_e32 v1, 5, v1
	s_add_u32 s51, s16, s2
	v_and_b32_e32 v16, 32, v1
	v_and_b32_e32 v1, 0xc0, v3
	s_addc_u32 s52, s17, 0
	s_mul_i32 s2, s23, s11
	v_sub_u32_e32 v0, v0, v1
	v_lshlrev_b32_e32 v1, 1, v2
	v_lshrrev_b32_e32 v3, 2, v2
	s_mul_hi_i32 s3, s23, s11
	s_add_u32 s2, s51, s2
	v_ashrrev_i16_sdwa v0, v235, sext(v0) dst_sel:DWORD dst_unused:UNUSED_PAD src0_sel:DWORD src1_sel:BYTE_0
	v_and_b32_e32 v1, 24, v1
	v_and_b32_e32 v3, 4, v3
	s_addc_u32 s3, s52, s3
	s_add_i32 s53, s50, 0
	v_bfe_i32 v17, v0, 0, 16
	v_or3_b32 v1, v4, v3, v1
	s_add_i32 m0, s53, 0x10000
	v_add_u32_e32 v0, v16, v17
	v_mul_u32_u24_e32 v1, s35, v1
	global_load_lds_dwordx4 v192, s[2:3]
	s_add_i32 m0, s53, 0x12000
	v_add_lshl_u32 v216, v1, v0, 1
	s_add_u32 s24, s2, s46
	global_load_lds_dwordx4 v216, s[2:3]
	s_addc_u32 s25, s3, 0
	s_add_i32 m0, s53, 0x14000
	s_mul_i32 s27, s23, s10
	global_load_lds_dwordx4 v192, s[24:25]
	s_add_i32 m0, s53, 0x16000
	s_mul_hi_i32 s26, s23, s10
	s_add_u32 s44, s9, s27
	v_mov_b32_e32 v217, v193
	s_addc_u32 s45, s8, s26
	s_add_i32 s54, s53, 0x2000
	v_mul_lo_u32 v18, v2, s35
	v_lshl_add_u64 v[4:5], s[24:25], 0, v[192:193]
	v_lshl_add_u64 v[6:7], s[24:25], 0, v[216:217]
	global_load_lds_dwordx4 v216, s[24:25]
	s_mov_b32 m0, s53
	s_add_u32 s24, s44, s46
	v_add_lshl_u32 v214, v0, v18, 1
	global_load_lds_dwordx4 v212, s[44:45]
	s_mov_b32 m0, s54
	s_addc_u32 s25, s45, 0
	s_add_i32 s55, s53, 0x4000
	global_load_lds_dwordx4 v214, s[44:45]
	s_mov_b32 m0, s55
	s_add_i32 s56, s53, 0x6000
	global_load_lds_dwordx4 v212, s[24:25]
	s_mov_b32 m0, s56
	v_mov_b32_e32 v213, v193
	global_load_lds_dwordx4 v214, s[24:25]
	v_mov_b32_e32 v215, v193
	s_cmp_eq_u32 s15, 1
	v_mov_b32_e32 v195, 1
	v_lshl_add_u64 v[0:1], s[2:3], 0, v[192:193]
	v_lshl_add_u64 v[2:3], s[2:3], 0, v[216:217]
	v_lshl_add_u64 v[8:9], s[44:45], 0, v[212:213]
	v_lshl_add_u64 v[10:11], s[44:45], 0, v[214:215]
	s_cselect_b64 s[24:25], -1, 0
	s_cmp_lg_u32 s15, 1
	s_cbranch_scc1 .LBB0_433
	s_barrier

; #define PG8_STAGE(bufoff, gbase, voff) do { _Pragma("unroll") for (int _i = 0; _i < 2; ++_i) \
;         __builtin_amdgcn_global_load_lds((const unsigned*)((const char*)(gbase) + (voff)[_i]), (PG8_LAS unsigned*)(lds + (bufoff) + ldsw + _i * 8192), 16, 0, 0); } while (0)
; #define PG8_LDA(dst, b, h) do { _Pragma("unroll") for (int m = 0; m < 4; ++m) _Pragma("unroll") for (int k = 0; k < 2; ++k) dst[m][k] = *(const PG8_LAS bf16x8*)(lds + PG8_SA(b, h) + aoff + m * 2048 + k * 1024); } while (0)
; #define PG8_LDB(dst, b, h) do { _Pragma("unroll") for (int n = 0; n < 2; ++n) _Pragma("unroll") for (int k = 0; k < 2; ++k) dst[n][k] = *(const PG8_LAS bf16x8*)(lds + PG8_SB(b, h) + boff + n * 2048 + k * 1024); } while (0)
; #define PG8_MMA(ai, bj, At, Bt) do { __builtin_amdgcn_s_setprio(1); _Pragma("unroll") for (int m = 0; m < 4; ++m) _Pragma("unroll") for (int n = 0; n < 2; ++n) _Pragma("unroll") for (int k = 0; k < 2; ++k) \
;         acc[ai][bj][m][n] = __builtin_amdgcn_mfma_f32_16x16x32_bf16(Bt[n][k], At[m][k], acc[ai][bj][m][n], 0, 0, 0); __builtin_amdgcn_s_setprio(0); } while (0)
; #define PG8_WAIT_V(n) asm volatile("s_waitcnt vmcnt(" #n ")" ::: "memory")
; #define PG8_BAR __builtin_amdgcn_s_barrier()
; template <class Epi, class Sched, bool ALIGN_EPI = false, bool SP2 = false>
; __device__ __forceinline__ void gemm_phase(PG8_LAS unsigned char* lds, const Gemm g, const Sched& S, const Epi& E, int tid_in) {
;     ...
;         for (int t = t_beg; t < t_end; t += 2) {
;             const bool last = (t == nt - 2);
;             const char* a1 = cA + (size_t)(t + 1) * kstep;
;             const char* a2 = last ? nA : cA + (size_t)(t + 2) * kstep; const char* b2 = last ? nB : cB + (size_t)(t + 2) * kstep;
;             const char* a3 = a2 + kstep; const char* b3 = b2 + kstep;
;             if (last && has_next) S.a_ready(nxt);
;             if constexpr (SP2) {
;             PG8_LDB(B0, 0, 0); PG8_LDB(B1, 0, 1); PG8_SCHED; PG8_LDA(At, 0, 0); PG8_STAGE(PG8_SA(1, 1), a1 + hstep, voffA);
;             PG8_WAIT_V(8); PG8_WAIT_L(0); PG8_BAR; PG8_MMA(0, 0, At, B0); PG8_MMA(0, 1, At, B1); PG8_BAR; PG8_SCHED;
;             PG8_LDA(At, 0, 1); PG8_STAGE(PG8_SB(0, 0), b2, voffB); PG8_STAGE(PG8_SB(0, 1), b2 + hstep, voffB); PG8_STAGE(PG8_SA(0, 0), a2, voffA);
;             PG8_WAIT_V(8); PG8_WAIT_L(0); PG8_BAR; PG8_MMA(1, 0, At, B0); PG8_MMA(1, 1, At, B1); PG8_BAR; PG8_SCHED;
.LBB0_447:
	s_add_i32 s44, s14, 2
	s_add_u32 s45, s2, 0x80
	s_addc_u32 s15, s3, 0
	s_add_i32 s91, 0, 0x10000
	s_cmp_eq_u32 s85, s14
	s_cselect_b32 s15, s35, s15
	s_cselect_b32 s14, s34, s45
	s_cselect_b32 s93, s37, s43
	s_cselect_b32 s92, s36, s42
	s_add_i32 s45, 0, 0x14000
	v_add_u32_e32 v140, s91, v209
	v_add_u32_e32 v156, s45, v209
	ds_read_b128 v[128:131], v140
	ds_read_b128 v[132:135], v140 offset:1024
	ds_read_b128 v[136:139], v140 offset:2048
	ds_read_b128 v[140:143], v140 offset:3072
	ds_read_b128 v[144:147], v156
	ds_read_b128 v[148:151], v156 offset:1024
	ds_read_b128 v[152:155], v156 offset:2048
	ds_read_b128 v[156:159], v156 offset:3072
	v_lshl_add_u64 v[196:197], s[2:3], 0, v[224:225]
	s_add_i32 m0, s53, 0xc000
	ds_read_b128 v[160:163], v194
	ds_read_b128 v[164:167], v194 offset:1024
	ds_read_b128 v[168:171], v194 offset:2048
	ds_read_b128 v[172:175], v194 offset:3072
	ds_read_b128 v[176:179], v194 offset:4096
	ds_read_b128 v[180:183], v194 offset:5120
	ds_read_b128 v[184:187], v194 offset:6144
	ds_read_b128 v[188:191], v194 offset:7168
	global_load_lds_dwordx4 v[196:197], off
	v_lshl_add_u64 v[196:197], s[2:3], 0, v[222:223]
	s_add_i32 m0, s53, 0xe000
	s_nop 0
	global_load_lds_dwordx4 v[196:197], off
	s_waitcnt vmcnt(8)
	s_waitcnt lgkmcnt(0)
	s_barrier
	s_setprio 1
	s_waitcnt lgkmcnt(0)
	v_mfma_f32_16x16x32_bf16 v[124:127], v[128:131], v[160:163], v[124:127]
	v_mfma_f32_16x16x32_bf16 v[120:123], v[136:139], v[160:163], v[120:123]
	v_mfma_f32_16x16x32_bf16 v[108:111], v[128:131], v[168:171], v[108:111]
	v_mfma_f32_16x16x32_bf16 v[104:107], v[136:139], v[168:171], v[104:107]
	v_mfma_f32_16x16x32_bf16 v[92:95], v[128:131], v[176:179], v[92:95]
	v_mfma_f32_16x16x32_bf16 v[88:91], v[136:139], v[176:179], v[88:91]
	v_mfma_f32_16x16x32_bf16 v[76:79], v[128:131], v[184:187], v[76:79]
	v_mfma_f32_16x16x32_bf16 v[72:75], v[136:139], v[184:187], v[72:75]
	v_mfma_f32_16x16x32_bf16 v[124:127], v[132:135], v[164:167], v[124:127]
	v_mfma_f32_16x16x32_bf16 v[120:123], v[140:143], v[164:167], v[120:123]
	v_mfma_f32_16x16x32_bf16 v[108:111], v[132:135], v[172:175], v[108:111]
	v_mfma_f32_16x16x32_bf16 v[104:107], v[140:143], v[172:175], v[104:107]
	v_mfma_f32_16x16x32_bf16 v[92:95], v[132:135], v[180:183], v[92:95]
	v_mfma_f32_16x16x32_bf16 v[88:91], v[140:143], v[180:183], v[88:91]
	v_mfma_f32_16x16x32_bf16 v[76:79], v[132:135], v[188:191], v[76:79]
	v_mfma_f32_16x16x32_bf16 v[72:75], v[140:143], v[188:191], v[72:75]
	s_setprio 0
	s_setprio 1
	v_mfma_f32_16x16x32_bf16 v[116:119], v[144:147], v[160:163], v[116:119]
	v_mfma_f32_16x16x32_bf16 v[112:115], v[152:155], v[160:163], v[112:115]
	v_mfma_f32_16x16x32_bf16 v[100:103], v[144:147], v[168:171], v[100:103]
	v_mfma_f32_16x16x32_bf16 v[96:99], v[152:155], v[168:171], v[96:99]
	v_mfma_f32_16x16x32_bf16 v[84:87], v[144:147], v[176:179], v[84:87]
	v_mfma_f32_16x16x32_bf16 v[80:83], v[152:155], v[176:179], v[80:83]
	v_mfma_f32_16x16x32_bf16 v[68:71], v[144:147], v[184:187], v[68:71]
	v_mfma_f32_16x16x32_bf16 v[64:67], v[152:155], v[184:187], v[64:67]
	v_mfma_f32_16x16x32_bf16 v[116:119], v[148:151], v[164:167], v[116:119]
	v_mfma_f32_16x16x32_bf16 v[112:115], v[156:159], v[164:167], v[112:115]
	v_mfma_f32_16x16x32_bf16 v[100:103], v[148:151], v[172:175], v[100:103]
	v_mfma_f32_16x16x32_bf16 v[96:99], v[156:159], v[172:175], v[96:99]
	v_mfma_f32_16x16x32_bf16 v[84:87], v[148:151], v[180:183], v[84:87]
	v_mfma_f32_16x16x32_bf16 v[80:83], v[156:159], v[180:183], v[80:83]
	v_mfma_f32_16x16x32_bf16 v[68:71], v[148:151], v[188:191], v[68:71]
	v_mfma_f32_16x16x32_bf16 v[64:67], v[156:159], v[188:191], v[64:67]
	s_setprio 0
	s_barrier
	s_add_i32 s91, s91, s50
	v_lshl_add_u64 v[196:197], s[92:93], 0, v[192:193]
	s_mov_b32 m0, s91
	ds_read_b128 v[160:163], v194 offset:16384
	ds_read_b128 v[164:167], v194 offset:17408
	ds_read_b128 v[168:171], v194 offset:18432
	ds_read_b128 v[172:175], v194 offset:19456
	ds_read_b128 v[176:179], v194 offset:20480
	ds_read_b128 v[180:183], v194 offset:21504
	ds_read_b128 v[184:187], v194 offset:22528
	ds_read_b128 v[188:191], v194 offset:23552
	global_load_lds_dwordx4 v[196:197], off
	s_add_i32 m0, s91, 0x2000
	v_lshl_add_u64 v[198:199], s[92:93], 0, v[216:217]
	s_add_u32 s92, s92, s46
	s_addc_u32 s93, s93, 0
	s_add_i32 s45, s45, s50
	global_load_lds_dwordx4 v[198:199], off
	v_lshl_add_u64 v[200:201], s[92:93], 0, v[192:193]
	s_mov_b32 m0, s45
	v_lshl_add_u64 v[202:203], s[92:93], 0, v[216:217]
	global_load_lds_dwordx4 v[200:201], off
	s_add_i32 m0, s45, 0x2000
	v_lshl_add_u64 v[226:227], s[14:15], 0, v[212:213]
	global_load_lds_dwordx4 v[202:203], off
	s_mov_b32 m0, s53
	v_lshl_add_u64 v[228:229], s[14:15], 0, v[214:215]
	global_load_lds_dwordx4 v[226:227], off
	s_mov_b32 m0, s54
	s_nop 0
	global_load_lds_dwordx4 v[228:229], off
	s_waitcnt vmcnt(8)
	s_waitcnt lgkmcnt(0)
	s_barrier
; #define PG8_STAGE(bufoff, gbase, voff) do { _Pragma("unroll") for (int _i = 0; _i < 2; ++_i) \
;         __builtin_amdgcn_global_load_lds((const unsigned*)((const char*)(gbase) + (voff)[_i]), (PG8_LAS unsigned*)(lds + (bufoff) + ldsw + _i * 8192), 16, 0, 0); } while (0)
; #define PG8_LDA(dst, b, h) do { _Pragma("unroll") for (int m = 0; m < 4; ++m) _Pragma("unroll") for (int k = 0; k < 2; ++k) dst[m][k] = *(const PG8_LAS bf16x8*)(lds + PG8_SA(b, h) + aoff + m * 2048 + k * 1024); } while (0)
; #define PG8_LDB(dst, b, h) do { _Pragma("unroll") for (int n = 0; n < 2; ++n) _Pragma("unroll") for (int k = 0; k < 2; ++k) dst[n][k] = *(const PG8_LAS bf16x8*)(lds + PG8_SB(b, h) + boff + n * 2048 + k * 1024); } while (0)
; #define PG8_MMA(ai, bj, At, Bt) do { __builtin_amdgcn_s_setprio(1); _Pragma("unroll") for (int m = 0; m < 4; ++m) _Pragma("unroll") for (int n = 0; n < 2; ++n) _Pragma("unroll") for (int k = 0; k < 2; ++k) \
;         acc[ai][bj][m][n] = __builtin_amdgcn_mfma_f32_16x16x32_bf16(Bt[n][k], At[m][k], acc[ai][bj][m][n], 0, 0, 0); __builtin_amdgcn_s_setprio(0); } while (0)
; #define PG8_WAIT_V(n) asm volatile("s_waitcnt vmcnt(" #n ")" ::: "memory")
; #define PG8_WAIT_L(n) asm volatile("s_waitcnt lgkmcnt(" #n ")" ::: "memory")
; #define PG8_BAR __builtin_amdgcn_s_barrier()
; #define PG8_SCHED __builtin_amdgcn_sched_barrier(0)
; template <class Epi, class Sched, bool ALIGN_EPI = false, bool SP2 = false>
; __device__ __forceinline__ void gemm_phase(PG8_LAS unsigned char* lds, const Gemm g, const Sched& S, const Epi& E, int tid_in) {
;     ...
;             PG8_WAIT_V(8); PG8_WAIT_L(0); PG8_BAR; PG8_MMA(1, 0, At, B0); PG8_MMA(1, 1, At, B1); PG8_BAR; PG8_SCHED;
;             PG8_LDB(B0, 1, 0); PG8_LDB(B1, 1, 1); PG8_SCHED; PG8_LDA(At, 1, 0); PG8_STAGE(PG8_SA(0, 1), a2 + hstep, voffA);
;             PG8_WAIT_V(8); PG8_WAIT_L(0); PG8_BAR; PG8_MMA(0, 0, At, B0); PG8_MMA(0, 1, At, B1); PG8_BAR; PG8_SCHED;
;             PG8_LDA(At, 1, 1); PG8_STAGE(PG8_SB(1, 0), b3, voffB); PG8_STAGE(PG8_SB(1, 1), b3 + hstep, voffB); PG8_STAGE(PG8_SA(1, 0), a3, voffA);
;             PG8_WAIT_V(8); PG8_WAIT_L(0); PG8_BAR; PG8_MMA(1, 0, At, B0); PG8_MMA(1, 1, At, B1); PG8_BAR; PG8_SCHED;
	s_setprio 1
	s_waitcnt lgkmcnt(0)
	v_mfma_f32_16x16x32_bf16 v[60:63], v[128:131], v[160:163], v[60:63]
	v_mfma_f32_16x16x32_bf16 v[56:59], v[136:139], v[160:163], v[56:59]
	v_mfma_f32_16x16x32_bf16 v[44:47], v[128:131], v[168:171], v[44:47]
	v_mfma_f32_16x16x32_bf16 v[40:43], v[136:139], v[168:171], v[40:43]
	v_mfma_f32_16x16x32_bf16 v[28:31], v[128:131], v[176:179], v[28:31]
	v_mfma_f32_16x16x32_bf16 v[24:27], v[136:139], v[176:179], v[24:27]
	v_mfma_f32_16x16x32_bf16 v[12:15], v[128:131], v[184:187], v[12:15]
	v_mfma_f32_16x16x32_bf16 v[8:11], v[136:139], v[184:187], v[8:11]
	v_mfma_f32_16x16x32_bf16 v[60:63], v[132:135], v[164:167], v[60:63]
	v_mfma_f32_16x16x32_bf16 v[56:59], v[140:143], v[164:167], v[56:59]
	v_mfma_f32_16x16x32_bf16 v[44:47], v[132:135], v[172:175], v[44:47]
	v_mfma_f32_16x16x32_bf16 v[40:43], v[140:143], v[172:175], v[40:43]
	v_mfma_f32_16x16x32_bf16 v[28:31], v[132:135], v[180:183], v[28:31]
	v_mfma_f32_16x16x32_bf16 v[24:27], v[140:143], v[180:183], v[24:27]
	v_mfma_f32_16x16x32_bf16 v[12:15], v[132:135], v[188:191], v[12:15]
	v_mfma_f32_16x16x32_bf16 v[8:11], v[140:143], v[188:191], v[8:11]
	s_setprio 0
	s_setprio 1
	v_mfma_f32_16x16x32_bf16 v[52:55], v[144:147], v[160:163], v[52:55]
	v_mfma_f32_16x16x32_bf16 v[48:51], v[152:155], v[160:163], v[48:51]
	v_mfma_f32_16x16x32_bf16 v[36:39], v[144:147], v[168:171], v[36:39]
	v_mfma_f32_16x16x32_bf16 v[32:35], v[152:155], v[168:171], v[32:35]
	v_mfma_f32_16x16x32_bf16 v[20:23], v[144:147], v[176:179], v[20:23]
	v_mfma_f32_16x16x32_bf16 v[16:19], v[152:155], v[176:179], v[16:19]
	v_mfma_f32_16x16x32_bf16 v[4:7], v[144:147], v[184:187], v[4:7]
	v_mfma_f32_16x16x32_bf16 v[0:3], v[152:155], v[184:187], v[0:3]
	v_mfma_f32_16x16x32_bf16 v[52:55], v[148:151], v[164:167], v[52:55]
	v_mfma_f32_16x16x32_bf16 v[48:51], v[156:159], v[164:167], v[48:51]
	v_mfma_f32_16x16x32_bf16 v[36:39], v[148:151], v[172:175], v[36:39]
	v_mfma_f32_16x16x32_bf16 v[32:35], v[156:159], v[172:175], v[32:35]
	v_mfma_f32_16x16x32_bf16 v[20:23], v[148:151], v[180:183], v[20:23]
	v_mfma_f32_16x16x32_bf16 v[16:19], v[156:159], v[180:183], v[16:19]
	v_mfma_f32_16x16x32_bf16 v[4:7], v[148:151], v[188:191], v[4:7]
	v_mfma_f32_16x16x32_bf16 v[0:3], v[156:159], v[188:191], v[0:3]
	s_setprio 0
	s_barrier
	s_add_i32 s45, 0, 0x18000
	s_add_i32 s91, 0, 0x1c000
	v_add_u32_e32 v140, s45, v209
	v_add_u32_e32 v156, s91, v209
	ds_read_b128 v[128:131], v140
	ds_read_b128 v[132:135], v140 offset:1024
	ds_read_b128 v[136:139], v140 offset:2048
	ds_read_b128 v[140:143], v140 offset:3072
	ds_read_b128 v[144:147], v156
	ds_read_b128 v[148:151], v156 offset:1024
	ds_read_b128 v[152:155], v156 offset:2048
	ds_read_b128 v[156:159], v156 offset:3072
	s_add_u32 s14, s14, s46
	s_addc_u32 s15, s15, 0
	s_mov_b32 m0, s55
	v_lshl_add_u64 v[230:231], s[14:15], 0, v[212:213]
	ds_read_b128 v[160:163], v194 offset:32768
	ds_read_b128 v[164:167], v194 offset:33792
	ds_read_b128 v[168:171], v194 offset:34816
	ds_read_b128 v[172:175], v194 offset:35840
	ds_read_b128 v[176:179], v194 offset:36864
	ds_read_b128 v[180:183], v194 offset:37888
	ds_read_b128 v[184:187], v194 offset:38912
	ds_read_b128 v[188:191], v194 offset:39936
	global_load_lds_dwordx4 v[230:231], off
	v_lshl_add_u64 v[230:231], s[14:15], 0, v[214:215]
	s_mov_b32 m0, s56
	s_nop 0
	global_load_lds_dwordx4 v[230:231], off
	s_waitcnt vmcnt(8)
	s_waitcnt lgkmcnt(0)
	s_barrier
	s_setprio 1
	s_waitcnt lgkmcnt(0)
	v_mfma_f32_16x16x32_bf16 v[124:127], v[128:131], v[160:163], v[124:127]
	v_mfma_f32_16x16x32_bf16 v[120:123], v[136:139], v[160:163], v[120:123]
	v_mfma_f32_16x16x32_bf16 v[108:111], v[128:131], v[168:171], v[108:111]
	v_mfma_f32_16x16x32_bf16 v[104:107], v[136:139], v[168:171], v[104:107]
	v_mfma_f32_16x16x32_bf16 v[92:95], v[128:131], v[176:179], v[92:95]
	v_mfma_f32_16x16x32_bf16 v[88:91], v[136:139], v[176:179], v[88:91]
	v_mfma_f32_16x16x32_bf16 v[76:79], v[128:131], v[184:187], v[76:79]
	v_mfma_f32_16x16x32_bf16 v[72:75], v[136:139], v[184:187], v[72:75]
	v_mfma_f32_16x16x32_bf16 v[124:127], v[132:135], v[164:167], v[124:127]
	v_mfma_f32_16x16x32_bf16 v[120:123], v[140:143], v[164:167], v[120:123]
	v_mfma_f32_16x16x32_bf16 v[108:111], v[132:135], v[172:175], v[108:111]
	v_mfma_f32_16x16x32_bf16 v[104:107], v[140:143], v[172:175], v[104:107]
	v_mfma_f32_16x16x32_bf16 v[92:95], v[132:135], v[180:183], v[92:95]
	v_mfma_f32_16x16x32_bf16 v[88:91], v[140:143], v[180:183], v[88:91]
	v_mfma_f32_16x16x32_bf16 v[76:79], v[132:135], v[188:191], v[76:79]
	v_mfma_f32_16x16x32_bf16 v[72:75], v[140:143], v[188:191], v[72:75]
	s_setprio 0
	s_setprio 1
	v_mfma_f32_16x16x32_bf16 v[116:119], v[144:147], v[160:163], v[116:119]
	v_mfma_f32_16x16x32_bf16 v[112:115], v[152:155], v[160:163], v[112:115]
	v_mfma_f32_16x16x32_bf16 v[100:103], v[144:147], v[168:171], v[100:103]
	v_mfma_f32_16x16x32_bf16 v[96:99], v[152:155], v[168:171], v[96:99]
	v_mfma_f32_16x16x32_bf16 v[84:87], v[144:147], v[176:179], v[84:87]
	v_mfma_f32_16x16x32_bf16 v[80:83], v[152:155], v[176:179], v[80:83]
	v_mfma_f32_16x16x32_bf16 v[68:71], v[144:147], v[184:187], v[68:71]
	v_mfma_f32_16x16x32_bf16 v[64:67], v[152:155], v[184:187], v[64:67]
	v_mfma_f32_16x16x32_bf16 v[116:119], v[148:151], v[164:167], v[116:119]
	v_mfma_f32_16x16x32_bf16 v[112:115], v[156:159], v[164:167], v[112:115]
	v_mfma_f32_16x16x32_bf16 v[100:103], v[148:151], v[172:175], v[100:103]
	v_mfma_f32_16x16x32_bf16 v[96:99], v[156:159], v[172:175], v[96:99]
	v_mfma_f32_16x16x32_bf16 v[84:87], v[148:151], v[180:183], v[84:87]
	v_mfma_f32_16x16x32_bf16 v[80:83], v[156:159], v[180:183], v[80:83]
	v_mfma_f32_16x16x32_bf16 v[68:71], v[148:151], v[188:191], v[68:71]
	v_mfma_f32_16x16x32_bf16 v[64:67], v[156:159], v[188:191], v[64:67]
	s_setprio 0
	s_barrier
; #define PG8_STAGE(bufoff, gbase, voff) do { _Pragma("unroll") for (int _i = 0; _i < 2; ++_i) \
;         __builtin_amdgcn_global_load_lds((const unsigned*)((const char*)(gbase) + (voff)[_i]), (PG8_LAS unsigned*)(lds + (bufoff) + ldsw + _i * 8192), 16, 0, 0); } while (0)
; #define PG8_LDA(dst, b, h) do { _Pragma("unroll") for (int m = 0; m < 4; ++m) _Pragma("unroll") for (int k = 0; k < 2; ++k) dst[m][k] = *(const PG8_LAS bf16x8*)(lds + PG8_SA(b, h) + aoff + m * 2048 + k * 1024); } while (0)
; #define PG8_BAR __builtin_amdgcn_s_barrier()
; template <class Epi, class Sched, bool ALIGN_EPI = false, bool SP2 = false>
; __device__ __forceinline__ void gemm_phase(PG8_LAS unsigned char* lds, const Gemm g, const Sched& S, const Epi& E, int tid_in) {
;     ...
;         if constexpr (Epi::HAS_MID) { if (hk == 1) E.mid(acc, cur, wr, fr); }
;         const int t_beg = hk * (nt / NHK), t_end = (hk + 1) * (nt / NHK);
;         for (int t = t_beg; t < t_end; t += 2) {
;             const bool last = (t == nt - 2);
;             const char* a1 = cA + (size_t)(t + 1) * kstep;
;             const char* a2 = last ? nA : cA + (size_t)(t + 2) * kstep; const char* b2 = last ? nB : cB + (size_t)(t + 2) * kstep;
;             const char* a3 = a2 + kstep; const char* b3 = b2 + kstep;
;             if (last && has_next) S.a_ready(nxt);
;             if constexpr (SP2) {
;             PG8_LDB(B0, 0, 0); PG8_LDB(B1, 0, 1); PG8_SCHED; PG8_LDA(At, 0, 0); PG8_STAGE(PG8_SA(1, 1), a1 + hstep, voffA);
;             PG8_WAIT_V(8); PG8_WAIT_L(0); PG8_BAR; PG8_MMA(0, 0, At, B0); PG8_MMA(0, 1, At, B1); PG8_BAR; PG8_SCHED;
;             PG8_LDA(At, 0, 1); PG8_STAGE(PG8_SB(0, 0), b2, voffB); PG8_STAGE(PG8_SB(0, 1), b2 + hstep, voffB); PG8_STAGE(PG8_SA(0, 0), a2, voffA);
;             PG8_WAIT_V(8); PG8_WAIT_L(0); PG8_BAR; PG8_MMA(1, 0, At, B0); PG8_MMA(1, 1, At, B1); PG8_BAR; PG8_SCHED;
;             PG8_LDB(B0, 1, 0); PG8_LDB(B1, 1, 1); PG8_SCHED; PG8_LDA(At, 1, 0); PG8_STAGE(PG8_SA(0, 1), a2 + hstep, voffA);
;             PG8_WAIT_V(8); PG8_WAIT_L(0); PG8_BAR; PG8_MMA(0, 0, At, B0); PG8_MMA(0, 1, At, B1); PG8_BAR; PG8_SCHED;
;             PG8_LDA(At, 1, 1); PG8_STAGE(PG8_SB(1, 0), b3, voffB); PG8_STAGE(PG8_SB(1, 1), b3 + hstep, voffB); PG8_STAGE(PG8_SA(1, 0), a3, voffA);
;             PG8_WAIT_V(8); PG8_WAIT_L(0); PG8_BAR; PG8_MMA(1, 0, At, B0); PG8_MMA(1, 1, At, B1); PG8_BAR; PG8_SCHED;
	s_add_i32 s14, s45, s50
	v_lshl_add_u64 v[196:197], v[196:197], 0, s[4:5]
	s_mov_b32 m0, s14
	ds_read_b128 v[160:163], v194 offset:49152
	ds_read_b128 v[164:167], v194 offset:50176
	ds_read_b128 v[168:171], v194 offset:51200
	ds_read_b128 v[172:175], v194 offset:52224
	ds_read_b128 v[176:179], v194 offset:53248
	ds_read_b128 v[180:183], v194 offset:54272
	ds_read_b128 v[184:187], v194 offset:55296
	ds_read_b128 v[188:191], v194 offset:56320
	global_load_lds_dwordx4 v[196:197], off
	v_lshl_add_u64 v[196:197], v[198:199], 0, s[4:5]
	s_add_i32 m0, s14, 0x2000
	s_add_i32 s14, s91, s50
	global_load_lds_dwordx4 v[196:197], off
	v_lshl_add_u64 v[196:197], v[200:201], 0, s[4:5]
	s_mov_b32 m0, s14
	s_nop 0
	global_load_lds_dwordx4 v[196:197], off
	v_lshl_add_u64 v[196:197], v[202:203], 0, s[4:5]
	s_add_i32 m0, s14, 0x2000
	s_nop 0
	global_load_lds_dwordx4 v[196:197], off
	v_lshl_add_u64 v[196:197], v[226:227], 0, s[4:5]
	s_mov_b32 m0, s57
	s_nop 0
	global_load_lds_dwordx4 v[196:197], off
	v_lshl_add_u64 v[196:197], v[228:229], 0, s[4:5]
	s_mov_b32 m0, s83
	s_nop 0
	global_load_lds_dwordx4 v[196:197], off
	s_waitcnt vmcnt(8)
	s_waitcnt lgkmcnt(0)
	s_barrier
	s_setprio 1
	s_waitcnt lgkmcnt(0)
	v_mfma_f32_16x16x32_bf16 v[60:63], v[128:131], v[160:163], v[60:63]
	v_mfma_f32_16x16x32_bf16 v[56:59], v[136:139], v[160:163], v[56:59]
	v_mfma_f32_16x16x32_bf16 v[44:47], v[128:131], v[168:171], v[44:47]
	v_mfma_f32_16x16x32_bf16 v[40:43], v[136:139], v[168:171], v[40:43]
	v_mfma_f32_16x16x32_bf16 v[28:31], v[128:131], v[176:179], v[28:31]
	v_mfma_f32_16x16x32_bf16 v[24:27], v[136:139], v[176:179], v[24:27]
	v_mfma_f32_16x16x32_bf16 v[12:15], v[128:131], v[184:187], v[12:15]
	v_mfma_f32_16x16x32_bf16 v[8:11], v[136:139], v[184:187], v[8:11]
	v_mfma_f32_16x16x32_bf16 v[60:63], v[132:135], v[164:167], v[60:63]
	v_mfma_f32_16x16x32_bf16 v[56:59], v[140:143], v[164:167], v[56:59]
	v_mfma_f32_16x16x32_bf16 v[44:47], v[132:135], v[172:175], v[44:47]
	v_mfma_f32_16x16x32_bf16 v[40:43], v[140:143], v[172:175], v[40:43]
	v_mfma_f32_16x16x32_bf16 v[28:31], v[132:135], v[180:183], v[28:31]
	v_mfma_f32_16x16x32_bf16 v[24:27], v[140:143], v[180:183], v[24:27]
	v_mfma_f32_16x16x32_bf16 v[12:15], v[132:135], v[188:191], v[12:15]
	v_mfma_f32_16x16x32_bf16 v[8:11], v[140:143], v[188:191], v[8:11]
	s_setprio 0
	s_setprio 1
	v_mfma_f32_16x16x32_bf16 v[52:55], v[144:147], v[160:163], v[52:55]
	v_mfma_f32_16x16x32_bf16 v[48:51], v[152:155], v[160:163], v[48:51]
	v_mfma_f32_16x16x32_bf16 v[36:39], v[144:147], v[168:171], v[36:39]
	v_mfma_f32_16x16x32_bf16 v[32:35], v[152:155], v[168:171], v[32:35]
	v_mfma_f32_16x16x32_bf16 v[20:23], v[144:147], v[176:179], v[20:23]
	v_mfma_f32_16x16x32_bf16 v[16:19], v[152:155], v[176:179], v[16:19]
	v_mfma_f32_16x16x32_bf16 v[4:7], v[144:147], v[184:187], v[4:7]
	v_mfma_f32_16x16x32_bf16 v[0:3], v[152:155], v[184:187], v[0:3]
	v_mfma_f32_16x16x32_bf16 v[52:55], v[148:151], v[164:167], v[52:55]
	v_mfma_f32_16x16x32_bf16 v[48:51], v[156:159], v[164:167], v[48:51]
	v_mfma_f32_16x16x32_bf16 v[36:39], v[148:151], v[172:175], v[36:39]
	v_mfma_f32_16x16x32_bf16 v[32:35], v[156:159], v[172:175], v[32:35]
	v_mfma_f32_16x16x32_bf16 v[20:23], v[148:151], v[180:183], v[20:23]
	v_mfma_f32_16x16x32_bf16 v[16:19], v[156:159], v[180:183], v[16:19]
	v_mfma_f32_16x16x32_bf16 v[4:7], v[148:151], v[188:191], v[4:7]
	v_mfma_f32_16x16x32_bf16 v[0:3], v[156:159], v[188:191], v[0:3]
	s_setprio 0
	s_barrier
	s_add_u32 s42, s42, 0x100
	s_addc_u32 s43, s43, 0
	s_add_u32 s2, s2, 0x100
	s_addc_u32 s3, s3, 0
	s_cmp_eq_u32 s44, s101
	s_cbranch_scc1 .Lmid_scale
.Lmid_back:
	s_cmp_ge_u32 s44, s84
	s_mov_b32 s14, s44
	s_cbranch_scc0 .LBB0_447
	s_and_b64 vcc, exec, s[28:29]
	s_cbranch_vccz .LBB0_450
	s_barrier
; __device__ __forceinline__ float rstd_of(float ss, float inv_n) { return __builtin_amdgcn_rsqf(ss * inv_n + RMS_EPS); }
; __device__ __forceinline__ unsigned pk2(float lo, float hi) { return pg8::cvt_pk_bf16(lo, hi); }
; __device__ __forceinline__ float bf_lo(unsigned w) { return __uint_as_float(w << 16); }
; __device__ __forceinline__ float bf_hi(unsigned w) { return __uint_as_float(w & 0xffff0000u); }
; __global__ void __launch_bounds__(NWAVES * 64, 2) mk_fwd(Args args) {
;     ...
;                 for (int q = 0; q < 4; ++q) { mr[q] = (m0 + q * NGW < M) ? m0 + q * NGW : m0; ra[q] = gld<float>(ssA + mr[q]); rb[q] = gld<float>(ssB + mr[q]); }
; #pragma unroll
;                 for (int q = 0; q < 4; ++q)
; #pragma unroll
;                     for (int j = 0; j < 4; ++j) w[q][j] = gld<u32x4>((const u32x4*)(Y + (size_t)mr[q] * D) + lane + 64 * j);
; #pragma unroll
;                 for (int q = 0; q < 4; ++q) {
;                     if (q == 0 || mr[q] != m0) {
;                         const float fa = pg8::rstd_of(ra[q], 1.0f / 1024.0f), fb = pg8::rstd_of(rb[q], 1.0f / 1024.0f);
; #pragma unroll
;                         for (int j = 0; j < 4; ++j) { const float r = j < 2 ? fa : fb; u32x4 v = w[q][j];
;                             v.x = pk2(bf_lo(v.x) * r, bf_hi(v.x) * r); v.y = pk2(bf_lo(v.y) * r, bf_hi(v.y) * r); v.z = pk2(bf_lo(v.z) * r, bf_hi(v.z) * r); v.w = pk2(bf_lo(v.w) * r, bf_hi(v.w) * r);
;                             gst<u32x4>((u32x4*)(Y + (size_t)mr[q] * D) + lane + 64 * j, v); }
.LBB0_450:
	s_cmp_eq_u32 s48, 7
	s_cbranch_scc0 .Lend_noscale
	s_nop 15
	v_lshl_add_u32 v144, s10, 8, v207
	v_lshlrev_b32_e32 v144, 2, v144
	s_add_u32 s98, s16, 0x30000
	s_addc_u32 s99, s17, 0
	global_load_dword v136, v144, s[98:99]
	global_load_dword v137, v144, s[98:99] offset:64
	global_load_dword v138, v144, s[98:99] offset:128
	global_load_dword v139, v144, s[98:99] offset:192
	global_load_dword v140, v144, s[98:99] offset:512
	global_load_dword v141, v144, s[98:99] offset:576
	global_load_dword v142, v144, s[98:99] offset:640
	global_load_dword v143, v144, s[98:99] offset:704
	s_waitcnt vmcnt(0)
	v_fmamk_f32 v136, v136, 0x3a800000, v246
	v_fmamk_f32 v137, v137, 0x3a800000, v246
	v_fmamk_f32 v138, v138, 0x3a800000, v246
	v_fmamk_f32 v139, v139, 0x3a800000, v246
	v_fmamk_f32 v140, v140, 0x3a800000, v246
	v_fmamk_f32 v141, v141, 0x3a800000, v246
	v_fmamk_f32 v142, v142, 0x3a800000, v246
	v_fmamk_f32 v143, v143, 0x3a800000, v246
	v_rsq_f32_e32 v136, v136
	v_rsq_f32_e32 v137, v137
	v_rsq_f32_e32 v138, v138
	v_rsq_f32_e32 v139, v139
	v_rsq_f32_e32 v140, v140
	v_rsq_f32_e32 v141, v141
	v_rsq_f32_e32 v142, v142
	v_rsq_f32_e32 v143, v143
	s_nop 1
	v_mul_f32_e32 v112, v136, v112
	v_mul_f32_e32 v113, v136, v113
	v_mul_f32_e32 v114, v136, v114
	v_mul_f32_e32 v115, v136, v115
	v_mul_f32_e32 v116, v136, v116
	v_mul_f32_e32 v117, v136, v117
	v_mul_f32_e32 v118, v136, v118
	v_mul_f32_e32 v119, v136, v119
	v_mul_f32_e32 v120, v136, v120
	v_mul_f32_e32 v121, v136, v121
	v_mul_f32_e32 v122, v136, v122
	v_mul_f32_e32 v123, v136, v123
	v_mul_f32_e32 v124, v136, v124
	v_mul_f32_e32 v125, v136, v125
	v_mul_f32_e32 v126, v136, v126
	v_mul_f32_e32 v127, v136, v127
	v_mul_f32_e32 v96, v137, v96
	v_mul_f32_e32 v97, v137, v97
	v_mul_f32_e32 v98, v137, v98
	v_mul_f32_e32 v99, v137, v99
	v_mul_f32_e32 v100, v137, v100
	v_mul_f32_e32 v101, v137, v101
	v_mul_f32_e32 v102, v137, v102
	v_mul_f32_e32 v103, v137, v103
	v_mul_f32_e32 v104, v137, v104
	v_mul_f32_e32 v105, v137, v105
	v_mul_f32_e32 v106, v137, v106
	v_mul_f32_e32 v107, v137, v107
	v_mul_f32_e32 v108, v137, v108
	v_mul_f32_e32 v109, v137, v109
	v_mul_f32_e32 v110, v137, v110
	v_mul_f32_e32 v111, v137, v111
	v_mul_f32_e32 v80, v138, v80
	v_mul_f32_e32 v81, v138, v81
	v_mul_f32_e32 v82, v138, v82
	v_mul_f32_e32 v83, v138, v83
	v_mul_f32_e32 v84, v138, v84
	v_mul_f32_e32 v85, v138, v85
	v_mul_f32_e32 v86, v138, v86
	v_mul_f32_e32 v87, v138, v87
	v_mul_f32_e32 v88, v138, v88
	v_mul_f32_e32 v89, v138, v89
	v_mul_f32_e32 v90, v138, v90
	v_mul_f32_e32 v91, v138, v91
	v_mul_f32_e32 v92, v138, v92
	v_mul_f32_e32 v93, v138, v93
	v_mul_f32_e32 v94, v138, v94
	v_mul_f32_e32 v95, v138, v95
	v_mul_f32_e32 v64, v139, v64
	v_mul_f32_e32 v65, v139, v65
	v_mul_f32_e32 v66, v139, v66
	v_mul_f32_e32 v67, v139, v67
	v_mul_f32_e32 v68, v139, v68
	v_mul_f32_e32 v69, v139, v69
	v_mul_f32_e32 v70, v139, v70
	v_mul_f32_e32 v71, v139, v71
	v_mul_f32_e32 v72, v139, v72
	v_mul_f32_e32 v73, v139, v73
	v_mul_f32_e32 v74, v139, v74
	v_mul_f32_e32 v75, v139, v75
	v_mul_f32_e32 v76, v139, v76
	v_mul_f32_e32 v77, v139, v77
	v_mul_f32_e32 v78, v139, v78
	v_mul_f32_e32 v79, v139, v79
	v_mul_f32_e32 v48, v140, v48
	v_mul_f32_e32 v49, v140, v49
	v_mul_f32_e32 v50, v140, v50
	v_mul_f32_e32 v51, v140, v51
	v_mul_f32_e32 v52, v140, v52
	v_mul_f32_e32 v53, v140, v53
	v_mul_f32_e32 v54, v140, v54
	v_mul_f32_e32 v55, v140, v55
	v_mul_f32_e32 v56, v140, v56
	v_mul_f32_e32 v57, v140, v57
	v_mul_f32_e32 v58, v140, v58
	v_mul_f32_e32 v59, v140, v59
	v_mul_f32_e32 v60, v140, v60
	v_mul_f32_e32 v61, v140, v61
	v_mul_f32_e32 v62, v140, v62
	v_mul_f32_e32 v63, v140, v63
	v_mul_f32_e32 v32, v141, v32
	v_mul_f32_e32 v33, v141, v33
	v_mul_f32_e32 v34, v141, v34
	v_mul_f32_e32 v35, v141, v35
	v_mul_f32_e32 v36, v141, v36
	v_mul_f32_e32 v37, v141, v37
	v_mul_f32_e32 v38, v141, v38
	v_mul_f32_e32 v39, v141, v39
	v_mul_f32_e32 v40, v141, v40
	v_mul_f32_e32 v41, v141, v41
	v_mul_f32_e32 v42, v141, v42
	v_mul_f32_e32 v43, v141, v43
	v_mul_f32_e32 v44, v141, v44
	v_mul_f32_e32 v45, v141, v45
	v_mul_f32_e32 v46, v141, v46
	v_mul_f32_e32 v47, v141, v47
	v_mul_f32_e32 v16, v142, v16
	v_mul_f32_e32 v17, v142, v17
	v_mul_f32_e32 v18, v142, v18
	v_mul_f32_e32 v19, v142, v19
	v_mul_f32_e32 v20, v142, v20
	v_mul_f32_e32 v21, v142, v21
	v_mul_f32_e32 v22, v142, v22
	v_mul_f32_e32 v23, v142, v23
	v_mul_f32_e32 v24, v142, v24
	v_mul_f32_e32 v25, v142, v25
	v_mul_f32_e32 v26, v142, v26
	v_mul_f32_e32 v27, v142, v27
	v_mul_f32_e32 v28, v142, v28
	v_mul_f32_e32 v29, v142, v29
	v_mul_f32_e32 v30, v142, v30
	v_mul_f32_e32 v31, v142, v31
	v_mul_f32_e32 v0, v143, v0
	v_mul_f32_e32 v1, v143, v1
	v_mul_f32_e32 v2, v143, v2
	v_mul_f32_e32 v3, v143, v3
	v_mul_f32_e32 v4, v143, v4
	v_mul_f32_e32 v5, v143, v5
	v_mul_f32_e32 v6, v143, v6
	v_mul_f32_e32 v7, v143, v7
	v_mul_f32_e32 v8, v143, v8
	v_mul_f32_e32 v9, v143, v9
	v_mul_f32_e32 v10, v143, v10
	v_mul_f32_e32 v11, v143, v11
	v_mul_f32_e32 v12, v143, v12
	v_mul_f32_e32 v13, v143, v13
	v_mul_f32_e32 v14, v143, v14
	v_mul_f32_e32 v15, v143, v15

; __device__ __forceinline__ float rstd_of(float ss, float inv_n) { return __builtin_amdgcn_rsqf(ss * inv_n + RMS_EPS); }
; __device__ __forceinline__ unsigned pk2(float lo, float hi) { return pg8::cvt_pk_bf16(lo, hi); }
; __device__ __forceinline__ float bf_lo(unsigned w) { return __uint_as_float(w << 16); }
; __device__ __forceinline__ float bf_hi(unsigned w) { return __uint_as_float(w & 0xffff0000u); }
; __global__ void __launch_bounds__(NWAVES * 64, 2) mk_fwd(Args args) {
;     ...
;                 for (int q = 0; q < 4; ++q) { mr[q] = (m0 + q * NGW < M) ? m0 + q * NGW : m0; ra[q] = gld<float>(ssA + mr[q]); rb[q] = gld<float>(ssB + mr[q]); }
; #pragma unroll
;                 for (int q = 0; q < 4; ++q)
; #pragma unroll
;                     for (int j = 0; j < 4; ++j) w[q][j] = gld<u32x4>((const u32x4*)(Y + (size_t)mr[q] * D) + lane + 64 * j);
; #pragma unroll
;                 for (int q = 0; q < 4; ++q) {
;                     if (q == 0 || mr[q] != m0) {
;                         const float fa = pg8::rstd_of(ra[q], 1.0f / 1024.0f), fb = pg8::rstd_of(rb[q], 1.0f / 1024.0f);
; #pragma unroll
;                         for (int j = 0; j < 4; ++j) { const float r = j < 2 ? fa : fb; u32x4 v = w[q][j];
;                             v.x = pk2(bf_lo(v.x) * r, bf_hi(v.x) * r); v.y = pk2(bf_lo(v.y) * r, bf_hi(v.y) * r); v.z = pk2(bf_lo(v.z) * r, bf_hi(v.z) * r); v.w = pk2(bf_lo(v.w) * r, bf_hi(v.w) * r);
;                             gst<u32x4>((u32x4*)(Y + (size_t)mr[q] * D) + lane + 64 * j, v); }
.Lmid_scale:
	s_nop 15
	v_lshl_add_u32 v144, s10, 8, v207
	v_lshlrev_b32_e32 v144, 2, v144
	s_add_u32 s98, s16, 0x20000
	s_addc_u32 s99, s17, 0
	global_load_dword v128, v144, s[98:99]
	global_load_dword v129, v144, s[98:99] offset:64
	global_load_dword v130, v144, s[98:99] offset:128
	global_load_dword v131, v144, s[98:99] offset:192
	global_load_dword v132, v144, s[98:99] offset:512
	global_load_dword v133, v144, s[98:99] offset:576
	global_load_dword v134, v144, s[98:99] offset:640
	global_load_dword v135, v144, s[98:99] offset:704
	s_add_u32 s98, s16, 0x30000
	s_addc_u32 s99, s17, 0
	global_load_dword v136, v144, s[98:99]
	global_load_dword v137, v144, s[98:99] offset:64
	global_load_dword v138, v144, s[98:99] offset:128
	global_load_dword v139, v144, s[98:99] offset:192
	global_load_dword v140, v144, s[98:99] offset:512
	global_load_dword v141, v144, s[98:99] offset:576
	global_load_dword v142, v144, s[98:99] offset:640
	global_load_dword v143, v144, s[98:99] offset:704
	s_waitcnt vmcnt(0)
	v_fmamk_f32 v128, v128, 0x3a800000, v246
	v_fmamk_f32 v129, v129, 0x3a800000, v246
	v_fmamk_f32 v130, v130, 0x3a800000, v246
	v_fmamk_f32 v131, v131, 0x3a800000, v246
	v_fmamk_f32 v132, v132, 0x3a800000, v246
	v_fmamk_f32 v133, v133, 0x3a800000, v246
	v_fmamk_f32 v134, v134, 0x3a800000, v246
	v_fmamk_f32 v135, v135, 0x3a800000, v246
	v_fmamk_f32 v136, v136, 0x3a800000, v246
	v_fmamk_f32 v137, v137, 0x3a800000, v246
	v_fmamk_f32 v138, v138, 0x3a800000, v246
	v_fmamk_f32 v139, v139, 0x3a800000, v246
	v_fmamk_f32 v140, v140, 0x3a800000, v246
	v_fmamk_f32 v141, v141, 0x3a800000, v246
	v_fmamk_f32 v142, v142, 0x3a800000, v246
	v_fmamk_f32 v143, v143, 0x3a800000, v246
	v_rsq_f32_e32 v128, v128
	v_rsq_f32_e32 v129, v129
	v_rsq_f32_e32 v130, v130
	v_rsq_f32_e32 v131, v131
	v_rsq_f32_e32 v132, v132
	v_rsq_f32_e32 v133, v133
	v_rsq_f32_e32 v134, v134
	v_rsq_f32_e32 v135, v135
	v_sqrt_f32_e32 v136, v136
	v_sqrt_f32_e32 v137, v137
	v_sqrt_f32_e32 v138, v138
	v_sqrt_f32_e32 v139, v139
	v_sqrt_f32_e32 v140, v140
	v_sqrt_f32_e32 v141, v141
	v_sqrt_f32_e32 v142, v142
	v_sqrt_f32_e32 v143, v143
	s_nop 1
	v_mul_f32_e32 v128, v128, v136
	v_mul_f32_e32 v129, v129, v137
	v_mul_f32_e32 v130, v130, v138
	v_mul_f32_e32 v131, v131, v139
	v_mul_f32_e32 v132, v132, v140
	v_mul_f32_e32 v133, v133, v141
	v_mul_f32_e32 v134, v134, v142
	v_mul_f32_e32 v135, v135, v143
	v_mul_f32_e32 v112, v128, v112
	v_mul_f32_e32 v113, v128, v113
	v_mul_f32_e32 v114, v128, v114
	v_mul_f32_e32 v115, v128, v115
	v_mul_f32_e32 v116, v128, v116
	v_mul_f32_e32 v117, v128, v117
	v_mul_f32_e32 v118, v128, v118
	v_mul_f32_e32 v119, v128, v119
	v_mul_f32_e32 v120, v128, v120
	v_mul_f32_e32 v121, v128, v121
	v_mul_f32_e32 v122, v128, v122
	v_mul_f32_e32 v123, v128, v123
	v_mul_f32_e32 v124, v128, v124
	v_mul_f32_e32 v125, v128, v125
	v_mul_f32_e32 v126, v128, v126
	v_mul_f32_e32 v127, v128, v127
	v_mul_f32_e32 v96, v129, v96
	v_mul_f32_e32 v97, v129, v97
	v_mul_f32_e32 v98, v129, v98
	v_mul_f32_e32 v99, v129, v99
	v_mul_f32_e32 v100, v129, v100
	v_mul_f32_e32 v101, v129, v101
	v_mul_f32_e32 v102, v129, v102
	v_mul_f32_e32 v103, v129, v103
	v_mul_f32_e32 v104, v129, v104
	v_mul_f32_e32 v105, v129, v105
	v_mul_f32_e32 v106, v129, v106
	v_mul_f32_e32 v107, v129, v107
	v_mul_f32_e32 v108, v129, v108
	v_mul_f32_e32 v109, v129, v109
	v_mul_f32_e32 v110, v129, v110
	v_mul_f32_e32 v111, v129, v111
	v_mul_f32_e32 v80, v130, v80
	v_mul_f32_e32 v81, v130, v81
	v_mul_f32_e32 v82, v130, v82
	v_mul_f32_e32 v83, v130, v83
	v_mul_f32_e32 v84, v130, v84
	v_mul_f32_e32 v85, v130, v85
	v_mul_f32_e32 v86, v130, v86
	v_mul_f32_e32 v87, v130, v87
	v_mul_f32_e32 v88, v130, v88
	v_mul_f32_e32 v89, v130, v89
	v_mul_f32_e32 v90, v130, v90
	v_mul_f32_e32 v91, v130, v91
	v_mul_f32_e32 v92, v130, v92
	v_mul_f32_e32 v93, v130, v93
	v_mul_f32_e32 v94, v130, v94
	v_mul_f32_e32 v95, v130, v95
	v_mul_f32_e32 v64, v131, v64
	v_mul_f32_e32 v65, v131, v65
	v_mul_f32_e32 v66, v131, v66
	v_mul_f32_e32 v67, v131, v67
	v_mul_f32_e32 v68, v131, v68
	v_mul_f32_e32 v69, v131, v69
	v_mul_f32_e32 v70, v131, v70
	v_mul_f32_e32 v71, v131, v71
	v_mul_f32_e32 v72, v131, v72
	v_mul_f32_e32 v73, v131, v73
	v_mul_f32_e32 v74, v131, v74
	v_mul_f32_e32 v75, v131, v75
	v_mul_f32_e32 v76, v131, v76
	v_mul_f32_e32 v77, v131, v77
	v_mul_f32_e32 v78, v131, v78
	v_mul_f32_e32 v79, v131, v79
	v_mul_f32_e32 v48, v132, v48
	v_mul_f32_e32 v49, v132, v49
	v_mul_f32_e32 v50, v132, v50
	v_mul_f32_e32 v51, v132, v51
	v_mul_f32_e32 v52, v132, v52
	v_mul_f32_e32 v53, v132, v53
	v_mul_f32_e32 v54, v132, v54
	v_mul_f32_e32 v55, v132, v55
	v_mul_f32_e32 v56, v132, v56
	v_mul_f32_e32 v57, v132, v57
	v_mul_f32_e32 v58, v132, v58
	v_mul_f32_e32 v59, v132, v59
	v_mul_f32_e32 v60, v132, v60
	v_mul_f32_e32 v61, v132, v61
	v_mul_f32_e32 v62, v132, v62
	v_mul_f32_e32 v63, v132, v63
	v_mul_f32_e32 v32, v133, v32
	v_mul_f32_e32 v33, v133, v33
	v_mul_f32_e32 v34, v133, v34
	v_mul_f32_e32 v35, v133, v35
	v_mul_f32_e32 v36, v133, v36
	v_mul_f32_e32 v37, v133, v37
	v_mul_f32_e32 v38, v133, v38
	v_mul_f32_e32 v39, v133, v39
	v_mul_f32_e32 v40, v133, v40
	v_mul_f32_e32 v41, v133, v41
	v_mul_f32_e32 v42, v133, v42
	v_mul_f32_e32 v43, v133, v43
	v_mul_f32_e32 v44, v133, v44
	v_mul_f32_e32 v45, v133, v45
	v_mul_f32_e32 v46, v133, v46
	v_mul_f32_e32 v47, v133, v47
	v_mul_f32_e32 v16, v134, v16
	v_mul_f32_e32 v17, v134, v17
	v_mul_f32_e32 v18, v134, v18
	v_mul_f32_e32 v19, v134, v19
	v_mul_f32_e32 v20, v134, v20
	v_mul_f32_e32 v21, v134, v21
	v_mul_f32_e32 v22, v134, v22
	v_mul_f32_e32 v23, v134, v23
	v_mul_f32_e32 v24, v134, v24
	v_mul_f32_e32 v25, v134, v25
	v_mul_f32_e32 v26, v134, v26
	v_mul_f32_e32 v27, v134, v27
	v_mul_f32_e32 v28, v134, v28
	v_mul_f32_e32 v29, v134, v29
	v_mul_f32_e32 v30, v134, v30
	v_mul_f32_e32 v31, v134, v31
	v_mul_f32_e32 v0, v135, v0
	v_mul_f32_e32 v1, v135, v1
	v_mul_f32_e32 v2, v135, v2
	v_mul_f32_e32 v3, v135, v3
	v_mul_f32_e32 v4, v135, v4
	v_mul_f32_e32 v5, v135, v5
	v_mul_f32_e32 v6, v135, v6
	v_mul_f32_e32 v7, v135, v7
	v_mul_f32_e32 v8, v135, v8
	v_mul_f32_e32 v9, v135, v9
	v_mul_f32_e32 v10, v135, v10
	v_mul_f32_e32 v11, v135, v11
	v_mul_f32_e32 v12, v135, v12
	v_mul_f32_e32 v13, v135, v13
	v_mul_f32_e32 v14, v135, v14
	v_mul_f32_e32 v15, v135, v15
	s_branch .Lmid_back

; __global__ void __launch_bounds__(NWAVES * 64, 2) mk_fwd(Args args) {
;     ...
;     for (int ph = ph_lo; ph < ph_hi; ++ph) {
;         KArgs ka = ka0; asm volatile("" : "+s"(ka));
;         int lane_ = (int)__builtin_amdgcn_mbcnt_hi(~0u, __builtin_amdgcn_mbcnt_lo(~0u, 0u)); asm volatile("" : "+v"(lane_));
;         int tid = wave0 * 64 + lane_;
;         unsigned char* ws = ka->ws; asm volatile("" : "+s"(ws));
;         int wave = wave0, bx = (int)blockIdx.x; asm volatile("" : "+s"(wave), "+s"(bx));
;         const int lane = lane_ & 63;
;         float* SS = (float*)(ws + WS_SS);
;         float *ssx = SS, *ssh1 = SS + 16384, *ssA = SS + 2 * 16384, *ssB = SS + 3 * 16384, *ssh2 = SS + 4 * 16384, *ssh3 = SS + 5 * 16384;
;         bf16_t* HB = (bf16_t*)(ws + WS_HB); bf16_t* Y = (bf16_t*)(ws + WS_Y); bf16_t* ACT = (bf16_t*)(ws + WS_ACT);
;         const int G = gridDim.x, gw = bx * NWAVES + wave, NGW = G * NWAVES;
;         if (ph == 0) {
.LBB0_479:
	s_add_i32 s48, s48, 1
	s_cmp_eq_u32 s48, 6
	s_cselect_b32 s48, 7, s48
	s_cmp_ge_i32 s48, s49
	s_mov_b64 s[0:1], -1
	s_cbranch_scc1 .LBB0_10
